# grid barrier: follower workgroups invalidate only L1 (sc0) after the XCD release; XCD leader waits for its L2 invalidate before releasing
# baseline (speedup 1.0000x reference)
.LBB0_709:
	s_or_b64 exec, exec, s[40:41]
	s_waitcnt vmcnt(0)
	buffer_inv sc0
	s_waitcnt vmcnt(0)

.LBB0_731:
	s_or_b64 exec, exec, s[20:21]
	s_mov_b64 s[20:21], exec
	v_mbcnt_lo_u32_b32 v0, s20, 0
	v_mbcnt_hi_u32_b32 v0, s21, v0
	v_cmp_eq_u32_e32 vcc, 0, v0
	s_waitcnt vmcnt(0)
	buffer_inv sc1
	s_waitcnt vmcnt(0)
	s_and_saveexec_b64 s[40:41], vcc
	s_cbranch_execz .Ltr_7
	s_bcnt1_i32_b64 s20, s[20:21]
	v_readlane_b32 s4, v252, 32
	v_mov_b32_e32 v0, s20
	v_readlane_b32 s5, v252, 33
	s_nop 4
	global_atomic_add v1, v0, s[4:5]
	s_branch .Ltr_7
